# baseline (speedup 1.0000x reference)
; #define A64_GLOAD(t) do { A64_IDX(); const char* Kt = (const char*)(Kg + (size_t)(t) * 64 * ldk); const char* Vt = (const char*)(Vg + (size_t)(t) * 64 * ldv); \
;         kreg0 = *(const u32x4*)(Kt + (unsigned)(kk0 * ldk + kc0 * 8) * 2u); if (k2) kreg1 = *(const u32x4*)(Kt + (unsigned)(kk1 * ldk + kc1 * 8) * 2u); vreg = *(const u32x4*)(Vt + (unsigned)(vk * ldv + vc * 8) * 2u); } while (0)
; #define A64_LWRITE(bo) do { A64_IDX(); *(LAS u32x4*)(lds + (bo) + kk0 * KP + kc0 * 16) = kreg0; if (k2) *(LAS u32x4*)(lds + (bo) + kk1 * KP + kc1 * 16) = kreg1; \
;         *(LAS u32x4*)(lds + (bo) + KBYTES + (vc >> 2) * 4096 + vk * 64 + (vc & 3) * 16) = vreg; } while (0)
; #define A64_KREAD(bo, half) do { _Pragma("unroll") for (int ds = 0; ds < NDS; ++ds) kf[ds] = *(const LAS bf16x8*)(lds + (bo) + kfr + (half) * 32 * KP + ds * 32); } while (0)
; #define A64_S(dst, q) do { _Pragma("unroll") for (int i = 0; i < 16; ++i) dst[i] = 0.f; _Pragma("unroll") for (int ds = 0; ds < NDS; ++ds) dst = __builtin_amdgcn_mfma_f32_32x32x16_bf16(kf[ds], q[ds], dst, 0, 0, 0); } while (0)
; #define A64_SB() __builtin_amdgcn_sched_barrier(0)
; template <int DQK>
; __device__ __forceinline__ void attn_unit64p(LAS char* lds, const bf16x8 (&qa)[DQK / 16], const bf16x8 (&qb)[DQK / 16],
;                                              const bf16_t* Kg, int ldk, const bf16_t* Vg, int ldv, int nt, bf16_t* Obase, int ldo, int ogb_off) {
;     ...
;     A64_GLOAD(0); A64_LWRITE(0);
;     __syncthreads();
;     if (nt > 1) A64_GLOAD(1);
;     A64_KREAD(0, 0);
; #pragma nounroll
;     for (int j = 0; j < 2 * nt; ++j) {
;         const int t = j >> 1, hf = j & 1;
;         const unsigned bo = (t & 1) * BUF, bn = ((t & 1) ^ 1) * BUF;
;         const unsigned vo = bo + hf * 2048;
;         const unsigned ko = hf ? bn : bo + 32 * KP;
;         A64_SB(); A64_S(sa, qa); A64_EXP(sb, lb0, lb1, pb);
;         A64_SB(); A64_PV(ob0, ob1, pb);
;         A64_SB(); A64_S(sb, qb); A64_EXP(sa, la0, la1, pa); A64_VREAD(vo, 0);
;         A64_SB(); A64_KREAD(ko, 0); A64_PV(oa0, oa1, pa);
;         A64_SB();
;         if (!hf) {
;             if (t + 1 < nt) A64_LWRITE(bn);
;             __syncthreads();
;             if (t + 2 < nt) A64_GLOAD(t + 2);
;         }
;     }
.Lp11_g1_pro:
	s_mov_b32 s24, 0x2000
	s_mov_b32 s25, 0
	v_lshl_add_u64 v[180:181], v[168:169], 0, s[24:25]
	global_load_dwordx4 v[104:107], v[180:181], off
	v_mov_b32_e32 v68, 0xf149f2ca
	v_mov_b32_e32 v69, v68
	v_mov_b32_e32 v70, v68
	v_mov_b32_e32 v71, v68
	v_mov_b32_e32 v72, v68
	v_mov_b32_e32 v73, v68
	v_mov_b32_e32 v74, v68
	v_mov_b32_e32 v75, v68
	v_mov_b32_e32 v76, v68
	v_mov_b32_e32 v77, v68
	v_mov_b32_e32 v78, v68
	v_mov_b32_e32 v79, v68
	v_mov_b32_e32 v64, 0
	v_mov_b32_e32 v65, 0
	v_mov_b32_e32 v66, 0
	v_mov_b32_e32 v67, 0
	v_mov_b32_e32 v230, 0
	v_mov_b32_e32 v231, 0
	v_mov_b32_e32 v214, 0
	v_mov_b32_e32 v215, 0
	v_mov_b32_e32 v216, 0
	v_mov_b32_e32 v217, 0
	v_mov_b32_e32 v218, 0
	v_mov_b32_e32 v219, 0
	v_mov_b32_e32 v220, 0
	v_mov_b32_e32 v221, 0
	v_mov_b32_e32 v248, 0
	v_mov_b32_e32 v249, 0
	v_mov_b32_e32 v250, 0
	v_mov_b32_e32 v251, 0
	v_mov_b32_e32 v252, 0
	v_mov_b32_e32 v253, 0
	v_mov_b32_e32 v254, 0
	v_mov_b32_e32 v255, 0
.Lp11_loop:
	s_waitcnt lgkmcnt(0)
	v_mfma_f32_32x32x16_bf16 v[80:95], v[182:185], v[128:131], 0
	v_exp_f32_e32 v68, v68
	v_add_f32_e32 v172, v172, v64
	v_exp_f32_e32 v69, v69
	v_add_f32_e32 v173, v173, v65
	v_mfma_f32_32x32x16_bf16 v[80:95], v[186:189], v[124:127], v[80:95]
	v_exp_f32_e32 v70, v70
	v_cvt_pk_bf16_f32 v232, v68, v69
	v_exp_f32_e32 v71, v71
	v_add_f32_e32 v172, v172, v66
	v_mfma_f32_32x32x16_bf16 v[80:95], v[190:193], v[120:123], v[80:95]
	v_exp_f32_e32 v72, v72
	v_cvt_pk_bf16_f32 v233, v70, v71
	v_exp_f32_e32 v73, v73
	v_add_f32_e32 v173, v173, v67
	v_mfma_f32_32x32x16_bf16 v[80:95], v[194:197], v[116:119], v[80:95]
	v_exp_f32_e32 v74, v74
	v_cvt_pk_bf16_f32 v234, v72, v73
	v_exp_f32_e32 v75, v75
	v_add_f32_e32 v172, v172, v68
	v_mfma_f32_32x32x16_bf16 v[80:95], v[198:201], v[108:111], v[80:95]
	v_exp_f32_e32 v76, v76
	v_cvt_pk_bf16_f32 v235, v74, v75
	v_exp_f32_e32 v77, v77
	v_add_f32_e32 v173, v173, v69
	v_mfma_f32_32x32x16_bf16 v[80:95], v[202:205], v[112:115], v[80:95]
	v_exp_f32_e32 v78, v78
	v_cvt_pk_bf16_f32 v236, v76, v77
	v_exp_f32_e32 v79, v79
	v_add_f32_e32 v172, v172, v70
	v_mfma_f32_32x32x16_bf16 v[16:31], v[248:251], v[230:233], v[16:31]
	ds_read_b64_tr_b16 v[248:249], v239 offset:13312
	ds_read_b64_tr_b16 v[250:251], v239 offset:13824
	v_cvt_pk_bf16_f32 v237, v78, v79
	v_add_f32_e32 v173, v173, v71
	v_add_f32_e32 v172, v172, v72
	v_add_f32_e32 v173, v173, v73
	v_mfma_f32_32x32x16_bf16 v[0:15], v[252:255], v[230:233], v[0:15]
	ds_read_b64_tr_b16 v[252:253], v239 offset:17408
	ds_read_b64_tr_b16 v[254:255], v239 offset:17920
	v_add_f32_e32 v172, v172, v74
	v_exp_f32_e32 v80, v80
	v_add_f32_e32 v173, v173, v75
	v_exp_f32_e32 v81, v81
	v_mfma_f32_32x32x16_bf16 v[16:31], v[214:217], v[234:237], v[16:31]
	ds_read_b64_tr_b16 v[214:215], v239 offset:14336
	ds_read_b64_tr_b16 v[216:217], v239 offset:14848
	v_add_f32_e32 v172, v172, v76
	v_exp_f32_e32 v82, v82
	v_add_f32_e32 v173, v173, v77
	v_cvt_pk_bf16_f32 v222, v80, v81
	v_mfma_f32_32x32x16_bf16 v[0:15], v[218:221], v[234:237], v[0:15]
	ds_read_b64_tr_b16 v[218:219], v239 offset:18432
	ds_read_b64_tr_b16 v[220:221], v239 offset:18944
	v_exp_f32_e32 v83, v83
	v_add_f32_e32 v172, v172, v78
	v_add_f32_e32 v173, v173, v79
	v_cvt_pk_bf16_f32 v223, v82, v83
	v_mfma_f32_32x32x16_bf16 v[64:79], v[182:185], v[132:135], 0
	ds_read_b128 v[182:185], v238 offset:6656
	v_exp_f32_e32 v84, v84
	v_add_f32_e32 v170, v170, v80
	v_exp_f32_e32 v85, v85
	v_add_f32_e32 v171, v171, v81
	v_mfma_f32_32x32x16_bf16 v[64:79], v[186:189], v[136:139], v[64:79]
	ds_read_b128 v[186:189], v238 offset:6688
	v_exp_f32_e32 v86, v86
	v_cvt_pk_bf16_f32 v224, v84, v85
	v_exp_f32_e32 v87, v87
	v_add_f32_e32 v170, v170, v82
	v_mfma_f32_32x32x16_bf16 v[64:79], v[190:193], v[140:143], v[64:79]
	ds_read_b128 v[190:193], v238 offset:6720
	v_exp_f32_e32 v88, v88
	v_cvt_pk_bf16_f32 v225, v86, v87
	v_exp_f32_e32 v89, v89
	v_add_f32_e32 v171, v171, v83
	v_mfma_f32_32x32x16_bf16 v[64:79], v[194:197], v[144:147], v[64:79]
	ds_read_b128 v[194:197], v238 offset:6752
	v_exp_f32_e32 v90, v90
	v_cvt_pk_bf16_f32 v226, v88, v89
	v_exp_f32_e32 v91, v91
	v_add_f32_e32 v170, v170, v84
	v_mfma_f32_32x32x16_bf16 v[64:79], v[198:201], v[148:151], v[64:79]
	ds_read_b128 v[198:201], v238 offset:6784
	v_exp_f32_e32 v92, v92
	v_cvt_pk_bf16_f32 v227, v90, v91
	v_exp_f32_e32 v93, v93
	v_add_f32_e32 v171, v171, v85
	v_mfma_f32_32x32x16_bf16 v[64:79], v[202:205], v[152:155], v[64:79]
	ds_read_b128 v[202:205], v238 offset:6816
	v_exp_f32_e32 v94, v94
	v_cvt_pk_bf16_f32 v228, v92, v93
	v_exp_f32_e32 v95, v95
	v_add_f32_e32 v170, v170, v86
	s_waitcnt lgkmcnt(6)
	v_mfma_f32_32x32x16_bf16 v[32:47], v[248:251], v[222:225], v[32:47]
	v_cvt_pk_bf16_f32 v229, v94, v95
	v_add_f32_e32 v171, v171, v87
	v_add_f32_e32 v170, v170, v88
	v_add_f32_e32 v171, v171, v89
	s_waitcnt vmcnt(0)
	ds_write_b128 v159, v[96:99] offset:21504
	s_cmp_eq_u64 s[0:1], 0
	v_mfma_f32_32x32x16_bf16 v[48:63], v[252:255], v[222:225], v[48:63]
	v_add_f32_e32 v170, v170, v90
	v_exp_f32_e32 v64, v64
	v_add_f32_e32 v171, v171, v91
	v_exp_f32_e32 v65, v65
	s_cbranch_scc1 .Lp11_w1_a0
	ds_write_b128 v212, v[100:103] offset:21504
.Lp11_w1_a0:
	ds_write_b128 v179, v[104:107] offset:34816
	v_mfma_f32_32x32x16_bf16 v[32:47], v[214:217], v[226:229], v[32:47]
	v_add_f32_e32 v170, v170, v92
	v_exp_f32_e32 v66, v66
	v_add_f32_e32 v171, v171, v93
	v_cvt_pk_bf16_f32 v230, v64, v65
	s_add_u32 s22, s22, 0x3000
	s_addc_u32 s23, s23, 0
	v_lshl_add_u64 v[180:181], v[180:181], 0, s[24:25]
	v_mfma_f32_32x32x16_bf16 v[48:63], v[218:221], v[226:229], v[48:63]
	v_exp_f32_e32 v67, v67
	v_add_f32_e32 v170, v170, v94
	v_add_f32_e32 v171, v171, v95
	v_cvt_pk_bf16_f32 v231, v66, v67
	global_load_dwordx4 v[96:99], v160, s[22:23]
	s_cmp_eq_u64 s[0:1], 0
	s_cbranch_scc1 .Lp11_g1_a0
	global_load_dwordx4 v[100:103], v166, s[22:23]
; #define A64_GLOAD(t) do { A64_IDX(); const char* Kt = (const char*)(Kg + (size_t)(t) * 64 * ldk); const char* Vt = (const char*)(Vg + (size_t)(t) * 64 * ldv); \
;         kreg0 = *(const u32x4*)(Kt + (unsigned)(kk0 * ldk + kc0 * 8) * 2u); if (k2) kreg1 = *(const u32x4*)(Kt + (unsigned)(kk1 * ldk + kc1 * 8) * 2u); vreg = *(const u32x4*)(Vt + (unsigned)(vk * ldv + vc * 8) * 2u); } while (0)
; #define A64_LWRITE(bo) do { A64_IDX(); *(LAS u32x4*)(lds + (bo) + kk0 * KP + kc0 * 16) = kreg0; if (k2) *(LAS u32x4*)(lds + (bo) + kk1 * KP + kc1 * 16) = kreg1; \
;         *(LAS u32x4*)(lds + (bo) + KBYTES + (vc >> 2) * 4096 + vk * 64 + (vc & 3) * 16) = vreg; } while (0)
; #define A64_KREAD(bo, half) do { _Pragma("unroll") for (int ds = 0; ds < NDS; ++ds) kf[ds] = *(const LAS bf16x8*)(lds + (bo) + kfr + (half) * 32 * KP + ds * 32); } while (0)
; #define A64_S(dst, q) do { _Pragma("unroll") for (int i = 0; i < 16; ++i) dst[i] = 0.f; _Pragma("unroll") for (int ds = 0; ds < NDS; ++ds) dst = __builtin_amdgcn_mfma_f32_32x32x16_bf16(kf[ds], q[ds], dst, 0, 0, 0); } while (0)
; #define A64_SB() __builtin_amdgcn_sched_barrier(0)
; template <int DQK>
; __device__ __forceinline__ void attn_unit64p(LAS char* lds, const bf16x8 (&qa)[DQK / 16], const bf16x8 (&qb)[DQK / 16],
;                                              const bf16_t* Kg, int ldk, const bf16_t* Vg, int ldv, int nt, bf16_t* Obase, int ldo, int ogb_off) {
;     ...
;     A64_GLOAD(0); A64_LWRITE(0);
;     __syncthreads();
;     if (nt > 1) A64_GLOAD(1);
;     A64_KREAD(0, 0);
; #pragma nounroll
;     for (int j = 0; j < 2 * nt; ++j) {
;         const int t = j >> 1, hf = j & 1;
;         const unsigned bo = (t & 1) * BUF, bn = ((t & 1) ^ 1) * BUF;
;         const unsigned vo = bo + hf * 2048;
;         const unsigned ko = hf ? bn : bo + 32 * KP;
;         A64_SB(); A64_S(sa, qa); A64_EXP(sb, lb0, lb1, pb);
;         A64_SB(); A64_PV(ob0, ob1, pb);
;         A64_SB(); A64_S(sb, qb); A64_EXP(sa, la0, la1, pa); A64_VREAD(vo, 0);
;         A64_SB(); A64_KREAD(ko, 0); A64_PV(oa0, oa1, pa);
;         A64_SB();
;         if (!hf) {
;             if (t + 1 < nt) A64_LWRITE(bn);
;             __syncthreads();
;             if (t + 2 < nt) A64_GLOAD(t + 2);
;         }
;     }
.Lp11_g1_a0:
	global_load_dwordx4 v[104:107], v[180:181], off
	s_waitcnt lgkmcnt(2)
	v_mfma_f32_32x32x16_bf16 v[80:95], v[182:185], v[128:131], 0
	v_exp_f32_e32 v68, v68
	v_add_f32_e32 v172, v172, v64
	v_exp_f32_e32 v69, v69
	v_add_f32_e32 v173, v173, v65
	v_mfma_f32_32x32x16_bf16 v[80:95], v[186:189], v[124:127], v[80:95]
	v_exp_f32_e32 v70, v70
	v_cvt_pk_bf16_f32 v232, v68, v69
	v_exp_f32_e32 v71, v71
	v_add_f32_e32 v172, v172, v66
	v_mfma_f32_32x32x16_bf16 v[80:95], v[190:193], v[120:123], v[80:95]
	v_exp_f32_e32 v72, v72
	v_cvt_pk_bf16_f32 v233, v70, v71
	v_exp_f32_e32 v73, v73
	v_add_f32_e32 v173, v173, v67
	v_mfma_f32_32x32x16_bf16 v[80:95], v[194:197], v[116:119], v[80:95]
	v_exp_f32_e32 v74, v74
	v_cvt_pk_bf16_f32 v234, v72, v73
	v_exp_f32_e32 v75, v75
	v_add_f32_e32 v172, v172, v68
	v_mfma_f32_32x32x16_bf16 v[80:95], v[198:201], v[108:111], v[80:95]
	v_exp_f32_e32 v76, v76
	v_cvt_pk_bf16_f32 v235, v74, v75
	v_exp_f32_e32 v77, v77
	v_add_f32_e32 v173, v173, v69
	v_mfma_f32_32x32x16_bf16 v[80:95], v[202:205], v[112:115], v[80:95]
	v_exp_f32_e32 v78, v78
	v_cvt_pk_bf16_f32 v236, v76, v77
	v_exp_f32_e32 v79, v79
	v_add_f32_e32 v172, v172, v70
	v_mfma_f32_32x32x16_bf16 v[16:31], v[248:251], v[230:233], v[16:31]
	ds_read_b64_tr_b16 v[248:249], v239 offset:15360
	ds_read_b64_tr_b16 v[250:251], v239 offset:15872
	v_cvt_pk_bf16_f32 v237, v78, v79
	v_add_f32_e32 v173, v173, v71
	v_add_f32_e32 v172, v172, v72
	v_add_f32_e32 v173, v173, v73
	v_mfma_f32_32x32x16_bf16 v[0:15], v[252:255], v[230:233], v[0:15]
	ds_read_b64_tr_b16 v[252:253], v239 offset:19456
	ds_read_b64_tr_b16 v[254:255], v239 offset:19968
	v_add_f32_e32 v172, v172, v74
	v_exp_f32_e32 v80, v80
	v_add_f32_e32 v173, v173, v75
	v_exp_f32_e32 v81, v81
	v_mfma_f32_32x32x16_bf16 v[16:31], v[214:217], v[234:237], v[16:31]
	ds_read_b64_tr_b16 v[214:215], v239 offset:16384
	ds_read_b64_tr_b16 v[216:217], v239 offset:16896
	v_add_f32_e32 v172, v172, v76
	v_exp_f32_e32 v82, v82
	v_add_f32_e32 v173, v173, v77
	v_cvt_pk_bf16_f32 v222, v80, v81
	v_mfma_f32_32x32x16_bf16 v[0:15], v[218:221], v[234:237], v[0:15]
	ds_read_b64_tr_b16 v[218:219], v239 offset:20480
	ds_read_b64_tr_b16 v[220:221], v239 offset:20992
	v_exp_f32_e32 v83, v83
	v_add_f32_e32 v172, v172, v78
	v_add_f32_e32 v173, v173, v79
	v_cvt_pk_bf16_f32 v223, v82, v83
	s_waitcnt lgkmcnt(8)
	s_barrier
	v_mfma_f32_32x32x16_bf16 v[64:79], v[182:185], v[132:135], 0
	ds_read_b128 v[182:185], v238 offset:21504
	v_exp_f32_e32 v84, v84
	v_add_f32_e32 v170, v170, v80
	v_exp_f32_e32 v85, v85
	v_add_f32_e32 v171, v171, v81
	v_mfma_f32_32x32x16_bf16 v[64:79], v[186:189], v[136:139], v[64:79]
	ds_read_b128 v[186:189], v238 offset:21536
	v_exp_f32_e32 v86, v86
	v_cvt_pk_bf16_f32 v224, v84, v85
	v_exp_f32_e32 v87, v87
	v_add_f32_e32 v170, v170, v82
	v_mfma_f32_32x32x16_bf16 v[64:79], v[190:193], v[140:143], v[64:79]
	ds_read_b128 v[190:193], v238 offset:21568
	v_exp_f32_e32 v88, v88
	v_cvt_pk_bf16_f32 v225, v86, v87
	v_exp_f32_e32 v89, v89
	v_add_f32_e32 v171, v171, v83
	v_mfma_f32_32x32x16_bf16 v[64:79], v[194:197], v[144:147], v[64:79]
	ds_read_b128 v[194:197], v238 offset:21600
	v_exp_f32_e32 v90, v90
	v_cvt_pk_bf16_f32 v226, v88, v89
	v_exp_f32_e32 v91, v91
	v_add_f32_e32 v170, v170, v84
	v_mfma_f32_32x32x16_bf16 v[64:79], v[198:201], v[148:151], v[64:79]
	ds_read_b128 v[198:201], v238 offset:21632
	v_exp_f32_e32 v92, v92
	v_cvt_pk_bf16_f32 v227, v90, v91
	v_exp_f32_e32 v93, v93
	v_add_f32_e32 v171, v171, v85
	v_mfma_f32_32x32x16_bf16 v[64:79], v[202:205], v[152:155], v[64:79]
	ds_read_b128 v[202:205], v238 offset:21664
	v_exp_f32_e32 v94, v94
	v_cvt_pk_bf16_f32 v228, v92, v93
	v_exp_f32_e32 v95, v95
	v_add_f32_e32 v170, v170, v86
	s_waitcnt lgkmcnt(6)
	v_mfma_f32_32x32x16_bf16 v[32:47], v[248:251], v[222:225], v[32:47]
	v_cvt_pk_bf16_f32 v229, v94, v95
	v_add_f32_e32 v171, v171, v87
	v_add_f32_e32 v170, v170, v88
	v_add_f32_e32 v171, v171, v89
	v_mfma_f32_32x32x16_bf16 v[48:63], v[252:255], v[222:225], v[48:63]
	v_add_f32_e32 v170, v170, v90
	v_exp_f32_e32 v64, v64
	v_add_f32_e32 v171, v171, v91
	v_exp_f32_e32 v65, v65
	v_mfma_f32_32x32x16_bf16 v[32:47], v[214:217], v[226:229], v[32:47]
	v_add_f32_e32 v170, v170, v92
	v_exp_f32_e32 v66, v66
	v_add_f32_e32 v171, v171, v93
	v_cvt_pk_bf16_f32 v230, v64, v65
	v_mfma_f32_32x32x16_bf16 v[48:63], v[218:221], v[226:229], v[48:63]
	v_exp_f32_e32 v67, v67
	v_add_f32_e32 v170, v170, v94
	v_add_f32_e32 v171, v171, v95
	v_cvt_pk_bf16_f32 v231, v66, v67
	s_add_i32 s4, s4, 1
	s_cmp_lt_u32 s4, s39
	s_cbranch_scc0 .Lp11_drain
; #define A64_GLOAD(t) do { A64_IDX(); const char* Kt = (const char*)(Kg + (size_t)(t) * 64 * ldk); const char* Vt = (const char*)(Vg + (size_t)(t) * 64 * ldv); \
;         kreg0 = *(const u32x4*)(Kt + (unsigned)(kk0 * ldk + kc0 * 8) * 2u); if (k2) kreg1 = *(const u32x4*)(Kt + (unsigned)(kk1 * ldk + kc1 * 8) * 2u); vreg = *(const u32x4*)(Vt + (unsigned)(vk * ldv + vc * 8) * 2u); } while (0)
; #define A64_LWRITE(bo) do { A64_IDX(); *(LAS u32x4*)(lds + (bo) + kk0 * KP + kc0 * 16) = kreg0; if (k2) *(LAS u32x4*)(lds + (bo) + kk1 * KP + kc1 * 16) = kreg1; \
;         *(LAS u32x4*)(lds + (bo) + KBYTES + (vc >> 2) * 4096 + vk * 64 + (vc & 3) * 16) = vreg; } while (0)
; #define A64_KREAD(bo, half) do { _Pragma("unroll") for (int ds = 0; ds < NDS; ++ds) kf[ds] = *(const LAS bf16x8*)(lds + (bo) + kfr + (half) * 32 * KP + ds * 32); } while (0)
; #define A64_S(dst, q) do { _Pragma("unroll") for (int i = 0; i < 16; ++i) dst[i] = 0.f; _Pragma("unroll") for (int ds = 0; ds < NDS; ++ds) dst = __builtin_amdgcn_mfma_f32_32x32x16_bf16(kf[ds], q[ds], dst, 0, 0, 0); } while (0)
; #define A64_SB() __builtin_amdgcn_sched_barrier(0)
; template <int DQK>
; __device__ __forceinline__ void attn_unit64p(LAS char* lds, const bf16x8 (&qa)[DQK / 16], const bf16x8 (&qb)[DQK / 16],
;                                              const bf16_t* Kg, int ldk, const bf16_t* Vg, int ldv, int nt, bf16_t* Obase, int ldo, int ogb_off) {
;     ...
;     A64_GLOAD(0); A64_LWRITE(0);
;     __syncthreads();
;     if (nt > 1) A64_GLOAD(1);
;     A64_KREAD(0, 0);
; #pragma nounroll
;     for (int j = 0; j < 2 * nt; ++j) {
;         const int t = j >> 1, hf = j & 1;
;         const unsigned bo = (t & 1) * BUF, bn = ((t & 1) ^ 1) * BUF;
;         const unsigned vo = bo + hf * 2048;
;         const unsigned ko = hf ? bn : bo + 32 * KP;
;         A64_SB(); A64_S(sa, qa); A64_EXP(sb, lb0, lb1, pb);
;         A64_SB(); A64_PV(ob0, ob1, pb);
;         A64_SB(); A64_S(sb, qb); A64_EXP(sa, la0, la1, pa); A64_VREAD(vo, 0);
;         A64_SB(); A64_KREAD(ko, 0); A64_PV(oa0, oa1, pa);
;         A64_SB();
;         if (!hf) {
;             if (t + 1 < nt) A64_LWRITE(bn);
;             __syncthreads();
;             if (t + 2 < nt) A64_GLOAD(t + 2);
;         }
;     }
	s_waitcnt lgkmcnt(0)
	v_mfma_f32_32x32x16_bf16 v[80:95], v[182:185], v[128:131], 0
	v_exp_f32_e32 v68, v68
	v_add_f32_e32 v172, v172, v64
	v_exp_f32_e32 v69, v69
	v_add_f32_e32 v173, v173, v65
	v_mfma_f32_32x32x16_bf16 v[80:95], v[186:189], v[124:127], v[80:95]
	v_exp_f32_e32 v70, v70
	v_cvt_pk_bf16_f32 v232, v68, v69
	v_exp_f32_e32 v71, v71
	v_add_f32_e32 v172, v172, v66
	v_mfma_f32_32x32x16_bf16 v[80:95], v[190:193], v[120:123], v[80:95]
	v_exp_f32_e32 v72, v72
	v_cvt_pk_bf16_f32 v233, v70, v71
	v_exp_f32_e32 v73, v73
	v_add_f32_e32 v173, v173, v67
	v_mfma_f32_32x32x16_bf16 v[80:95], v[194:197], v[116:119], v[80:95]
	v_exp_f32_e32 v74, v74
	v_cvt_pk_bf16_f32 v234, v72, v73
	v_exp_f32_e32 v75, v75
	v_add_f32_e32 v172, v172, v68
	v_mfma_f32_32x32x16_bf16 v[80:95], v[198:201], v[108:111], v[80:95]
	v_exp_f32_e32 v76, v76
	v_cvt_pk_bf16_f32 v235, v74, v75
	v_exp_f32_e32 v77, v77
	v_add_f32_e32 v173, v173, v69
	v_mfma_f32_32x32x16_bf16 v[80:95], v[202:205], v[112:115], v[80:95]
	v_exp_f32_e32 v78, v78
	v_cvt_pk_bf16_f32 v236, v76, v77
	v_exp_f32_e32 v79, v79
	v_add_f32_e32 v172, v172, v70
	v_mfma_f32_32x32x16_bf16 v[16:31], v[248:251], v[230:233], v[16:31]
	ds_read_b64_tr_b16 v[248:249], v239 offset:34816
	ds_read_b64_tr_b16 v[250:251], v239 offset:35328
	v_cvt_pk_bf16_f32 v237, v78, v79
	v_add_f32_e32 v173, v173, v71
	v_add_f32_e32 v172, v172, v72
	v_add_f32_e32 v173, v173, v73
	v_mfma_f32_32x32x16_bf16 v[0:15], v[252:255], v[230:233], v[0:15]
	ds_read_b64_tr_b16 v[252:253], v239 offset:38912
	ds_read_b64_tr_b16 v[254:255], v239 offset:39424
	v_add_f32_e32 v172, v172, v74
	v_exp_f32_e32 v80, v80
	v_add_f32_e32 v173, v173, v75
	v_exp_f32_e32 v81, v81
	v_mfma_f32_32x32x16_bf16 v[16:31], v[214:217], v[234:237], v[16:31]
	ds_read_b64_tr_b16 v[214:215], v239 offset:35840
	ds_read_b64_tr_b16 v[216:217], v239 offset:36352
	v_add_f32_e32 v172, v172, v76
	v_exp_f32_e32 v82, v82
	v_add_f32_e32 v173, v173, v77
	v_cvt_pk_bf16_f32 v222, v80, v81
	v_mfma_f32_32x32x16_bf16 v[0:15], v[218:221], v[234:237], v[0:15]
	ds_read_b64_tr_b16 v[218:219], v239 offset:39936
	ds_read_b64_tr_b16 v[220:221], v239 offset:40448
	v_exp_f32_e32 v83, v83
	v_add_f32_e32 v172, v172, v78
	v_add_f32_e32 v173, v173, v79
	v_cvt_pk_bf16_f32 v223, v82, v83
	v_mfma_f32_32x32x16_bf16 v[64:79], v[182:185], v[132:135], 0
	ds_read_b128 v[182:185], v238 offset:28160
	v_exp_f32_e32 v84, v84
	v_add_f32_e32 v170, v170, v80
	v_exp_f32_e32 v85, v85
	v_add_f32_e32 v171, v171, v81
	v_mfma_f32_32x32x16_bf16 v[64:79], v[186:189], v[136:139], v[64:79]
	ds_read_b128 v[186:189], v238 offset:28192
	v_exp_f32_e32 v86, v86
	v_cvt_pk_bf16_f32 v224, v84, v85
	v_exp_f32_e32 v87, v87
	v_add_f32_e32 v170, v170, v82
	v_mfma_f32_32x32x16_bf16 v[64:79], v[190:193], v[140:143], v[64:79]
	ds_read_b128 v[190:193], v238 offset:28224
	v_exp_f32_e32 v88, v88
	v_cvt_pk_bf16_f32 v225, v86, v87
	v_exp_f32_e32 v89, v89
	v_add_f32_e32 v171, v171, v83
	v_mfma_f32_32x32x16_bf16 v[64:79], v[194:197], v[144:147], v[64:79]
	ds_read_b128 v[194:197], v238 offset:28256
	v_exp_f32_e32 v90, v90
	v_cvt_pk_bf16_f32 v226, v88, v89
	v_exp_f32_e32 v91, v91
	v_add_f32_e32 v170, v170, v84
	v_mfma_f32_32x32x16_bf16 v[64:79], v[198:201], v[148:151], v[64:79]
	ds_read_b128 v[198:201], v238 offset:28288
	v_exp_f32_e32 v92, v92
	v_cvt_pk_bf16_f32 v227, v90, v91
	v_exp_f32_e32 v93, v93
	v_add_f32_e32 v171, v171, v85
	v_mfma_f32_32x32x16_bf16 v[64:79], v[202:205], v[152:155], v[64:79]
	ds_read_b128 v[202:205], v238 offset:28320
	v_exp_f32_e32 v94, v94
	v_cvt_pk_bf16_f32 v228, v92, v93
	v_exp_f32_e32 v95, v95
	v_add_f32_e32 v170, v170, v86
	s_waitcnt lgkmcnt(6)
	v_mfma_f32_32x32x16_bf16 v[32:47], v[248:251], v[222:225], v[32:47]
	v_cvt_pk_bf16_f32 v229, v94, v95
	v_add_f32_e32 v171, v171, v87
	v_add_f32_e32 v170, v170, v88
	v_add_f32_e32 v171, v171, v89
	s_waitcnt vmcnt(0)
	ds_write_b128 v159, v[96:99] offset:43008
	s_cmp_eq_u64 s[0:1], 0
	v_mfma_f32_32x32x16_bf16 v[48:63], v[252:255], v[222:225], v[48:63]
	v_add_f32_e32 v170, v170, v90
	v_exp_f32_e32 v64, v64
	v_add_f32_e32 v171, v171, v91
	v_exp_f32_e32 v65, v65
	s_cbranch_scc1 .Lp11_w1_a1
	ds_write_b128 v212, v[100:103] offset:43008
.Lp11_w1_a1:
	ds_write_b128 v179, v[104:107] offset:56320
	v_mfma_f32_32x32x16_bf16 v[32:47], v[214:217], v[226:229], v[32:47]
	v_add_f32_e32 v170, v170, v92
	v_exp_f32_e32 v66, v66
	v_add_f32_e32 v171, v171, v93
	v_cvt_pk_bf16_f32 v230, v64, v65
	s_add_u32 s22, s22, 0x3000
	s_addc_u32 s23, s23, 0
	v_lshl_add_u64 v[180:181], v[180:181], 0, s[24:25]
	v_mfma_f32_32x32x16_bf16 v[48:63], v[218:221], v[226:229], v[48:63]
	v_exp_f32_e32 v67, v67
	v_add_f32_e32 v170, v170, v94
	v_add_f32_e32 v171, v171, v95
	v_cvt_pk_bf16_f32 v231, v66, v67
	global_load_dwordx4 v[96:99], v160, s[22:23]
	s_cmp_eq_u64 s[0:1], 0
	s_cbranch_scc1 .Lp11_g1_a1
	global_load_dwordx4 v[100:103], v166, s[22:23]
; #define A64_GLOAD(t) do { A64_IDX(); const char* Kt = (const char*)(Kg + (size_t)(t) * 64 * ldk); const char* Vt = (const char*)(Vg + (size_t)(t) * 64 * ldv); \
;         kreg0 = *(const u32x4*)(Kt + (unsigned)(kk0 * ldk + kc0 * 8) * 2u); if (k2) kreg1 = *(const u32x4*)(Kt + (unsigned)(kk1 * ldk + kc1 * 8) * 2u); vreg = *(const u32x4*)(Vt + (unsigned)(vk * ldv + vc * 8) * 2u); } while (0)
; #define A64_LWRITE(bo) do { A64_IDX(); *(LAS u32x4*)(lds + (bo) + kk0 * KP + kc0 * 16) = kreg0; if (k2) *(LAS u32x4*)(lds + (bo) + kk1 * KP + kc1 * 16) = kreg1; \
;         *(LAS u32x4*)(lds + (bo) + KBYTES + (vc >> 2) * 4096 + vk * 64 + (vc & 3) * 16) = vreg; } while (0)
; #define A64_KREAD(bo, half) do { _Pragma("unroll") for (int ds = 0; ds < NDS; ++ds) kf[ds] = *(const LAS bf16x8*)(lds + (bo) + kfr + (half) * 32 * KP + ds * 32); } while (0)
; #define A64_S(dst, q) do { _Pragma("unroll") for (int i = 0; i < 16; ++i) dst[i] = 0.f; _Pragma("unroll") for (int ds = 0; ds < NDS; ++ds) dst = __builtin_amdgcn_mfma_f32_32x32x16_bf16(kf[ds], q[ds], dst, 0, 0, 0); } while (0)
; #define A64_SB() __builtin_amdgcn_sched_barrier(0)
; template <int DQK>
; __device__ __forceinline__ void attn_unit64p(LAS char* lds, const bf16x8 (&qa)[DQK / 16], const bf16x8 (&qb)[DQK / 16],
;                                              const bf16_t* Kg, int ldk, const bf16_t* Vg, int ldv, int nt, bf16_t* Obase, int ldo, int ogb_off) {
;     ...
;     A64_GLOAD(0); A64_LWRITE(0);
;     __syncthreads();
;     if (nt > 1) A64_GLOAD(1);
;     A64_KREAD(0, 0);
; #pragma nounroll
;     for (int j = 0; j < 2 * nt; ++j) {
;         const int t = j >> 1, hf = j & 1;
;         const unsigned bo = (t & 1) * BUF, bn = ((t & 1) ^ 1) * BUF;
;         const unsigned vo = bo + hf * 2048;
;         const unsigned ko = hf ? bn : bo + 32 * KP;
;         A64_SB(); A64_S(sa, qa); A64_EXP(sb, lb0, lb1, pb);
;         A64_SB(); A64_PV(ob0, ob1, pb);
;         A64_SB(); A64_S(sb, qb); A64_EXP(sa, la0, la1, pa); A64_VREAD(vo, 0);
;         A64_SB(); A64_KREAD(ko, 0); A64_PV(oa0, oa1, pa);
;         A64_SB();
;         if (!hf) {
;             if (t + 1 < nt) A64_LWRITE(bn);
;             __syncthreads();
;             if (t + 2 < nt) A64_GLOAD(t + 2);
;         }
;     }
.Lp11_g1_a1:
	global_load_dwordx4 v[104:107], v[180:181], off
	s_waitcnt lgkmcnt(2)
	v_mfma_f32_32x32x16_bf16 v[80:95], v[182:185], v[128:131], 0
	v_exp_f32_e32 v68, v68
	v_add_f32_e32 v172, v172, v64
	v_exp_f32_e32 v69, v69
	v_add_f32_e32 v173, v173, v65
	v_mfma_f32_32x32x16_bf16 v[80:95], v[186:189], v[124:127], v[80:95]
	v_exp_f32_e32 v70, v70
	v_cvt_pk_bf16_f32 v232, v68, v69
	v_exp_f32_e32 v71, v71
	v_add_f32_e32 v172, v172, v66
	v_mfma_f32_32x32x16_bf16 v[80:95], v[190:193], v[120:123], v[80:95]
	v_exp_f32_e32 v72, v72
	v_cvt_pk_bf16_f32 v233, v70, v71
	v_exp_f32_e32 v73, v73
	v_add_f32_e32 v173, v173, v67
	v_mfma_f32_32x32x16_bf16 v[80:95], v[194:197], v[116:119], v[80:95]
	v_exp_f32_e32 v74, v74
	v_cvt_pk_bf16_f32 v234, v72, v73
	v_exp_f32_e32 v75, v75
	v_add_f32_e32 v172, v172, v68
	v_mfma_f32_32x32x16_bf16 v[80:95], v[198:201], v[108:111], v[80:95]
	v_exp_f32_e32 v76, v76
	v_cvt_pk_bf16_f32 v235, v74, v75
	v_exp_f32_e32 v77, v77
	v_add_f32_e32 v173, v173, v69
	v_mfma_f32_32x32x16_bf16 v[80:95], v[202:205], v[112:115], v[80:95]
	v_exp_f32_e32 v78, v78
	v_cvt_pk_bf16_f32 v236, v76, v77
	v_exp_f32_e32 v79, v79
	v_add_f32_e32 v172, v172, v70
	v_mfma_f32_32x32x16_bf16 v[16:31], v[248:251], v[230:233], v[16:31]
	ds_read_b64_tr_b16 v[248:249], v239 offset:36864
	ds_read_b64_tr_b16 v[250:251], v239 offset:37376
	v_cvt_pk_bf16_f32 v237, v78, v79
	v_add_f32_e32 v173, v173, v71
	v_add_f32_e32 v172, v172, v72
	v_add_f32_e32 v173, v173, v73
	v_mfma_f32_32x32x16_bf16 v[0:15], v[252:255], v[230:233], v[0:15]
	ds_read_b64_tr_b16 v[252:253], v239 offset:40960
	ds_read_b64_tr_b16 v[254:255], v239 offset:41472
	v_add_f32_e32 v172, v172, v74
	v_exp_f32_e32 v80, v80
	v_add_f32_e32 v173, v173, v75
	v_exp_f32_e32 v81, v81
	v_mfma_f32_32x32x16_bf16 v[16:31], v[214:217], v[234:237], v[16:31]
	ds_read_b64_tr_b16 v[214:215], v239 offset:37888
	ds_read_b64_tr_b16 v[216:217], v239 offset:38400
	v_add_f32_e32 v172, v172, v76
	v_exp_f32_e32 v82, v82
	v_add_f32_e32 v173, v173, v77
	v_cvt_pk_bf16_f32 v222, v80, v81
	v_mfma_f32_32x32x16_bf16 v[0:15], v[218:221], v[234:237], v[0:15]
	ds_read_b64_tr_b16 v[218:219], v239 offset:41984
	ds_read_b64_tr_b16 v[220:221], v239 offset:42496
	v_exp_f32_e32 v83, v83
	v_add_f32_e32 v172, v172, v78
	v_add_f32_e32 v173, v173, v79
	v_cvt_pk_bf16_f32 v223, v82, v83
	s_waitcnt lgkmcnt(8)
	s_barrier
	v_mfma_f32_32x32x16_bf16 v[64:79], v[182:185], v[132:135], 0
	ds_read_b128 v[182:185], v238 offset:43008
	v_exp_f32_e32 v84, v84
	v_add_f32_e32 v170, v170, v80
	v_exp_f32_e32 v85, v85
	v_add_f32_e32 v171, v171, v81
	v_mfma_f32_32x32x16_bf16 v[64:79], v[186:189], v[136:139], v[64:79]
	ds_read_b128 v[186:189], v238 offset:43040
	v_exp_f32_e32 v86, v86
	v_cvt_pk_bf16_f32 v224, v84, v85
	v_exp_f32_e32 v87, v87
	v_add_f32_e32 v170, v170, v82
	v_mfma_f32_32x32x16_bf16 v[64:79], v[190:193], v[140:143], v[64:79]
	ds_read_b128 v[190:193], v238 offset:43072
	v_exp_f32_e32 v88, v88
	v_cvt_pk_bf16_f32 v225, v86, v87
	v_exp_f32_e32 v89, v89
	v_add_f32_e32 v171, v171, v83
	v_mfma_f32_32x32x16_bf16 v[64:79], v[194:197], v[144:147], v[64:79]
	ds_read_b128 v[194:197], v238 offset:43104
	v_exp_f32_e32 v90, v90
	v_cvt_pk_bf16_f32 v226, v88, v89
	v_exp_f32_e32 v91, v91
	v_add_f32_e32 v170, v170, v84
	v_mfma_f32_32x32x16_bf16 v[64:79], v[198:201], v[148:151], v[64:79]
	ds_read_b128 v[198:201], v238 offset:43136
	v_exp_f32_e32 v92, v92
	v_cvt_pk_bf16_f32 v227, v90, v91
	v_exp_f32_e32 v93, v93
	v_add_f32_e32 v171, v171, v85
	v_mfma_f32_32x32x16_bf16 v[64:79], v[202:205], v[152:155], v[64:79]
	ds_read_b128 v[202:205], v238 offset:43168
	v_exp_f32_e32 v94, v94
	v_cvt_pk_bf16_f32 v228, v92, v93
	v_exp_f32_e32 v95, v95
	v_add_f32_e32 v170, v170, v86
	s_waitcnt lgkmcnt(6)
	v_mfma_f32_32x32x16_bf16 v[32:47], v[248:251], v[222:225], v[32:47]
	v_cvt_pk_bf16_f32 v229, v94, v95
	v_add_f32_e32 v171, v171, v87
	v_add_f32_e32 v170, v170, v88
	v_add_f32_e32 v171, v171, v89
	v_mfma_f32_32x32x16_bf16 v[48:63], v[252:255], v[222:225], v[48:63]
	v_add_f32_e32 v170, v170, v90
	v_exp_f32_e32 v64, v64
	v_add_f32_e32 v171, v171, v91
	v_exp_f32_e32 v65, v65
	v_mfma_f32_32x32x16_bf16 v[32:47], v[214:217], v[226:229], v[32:47]
	v_add_f32_e32 v170, v170, v92
	v_exp_f32_e32 v66, v66
	v_add_f32_e32 v171, v171, v93
	v_cvt_pk_bf16_f32 v230, v64, v65
	v_mfma_f32_32x32x16_bf16 v[48:63], v[218:221], v[226:229], v[48:63]
	v_exp_f32_e32 v67, v67
	v_add_f32_e32 v170, v170, v94
	v_add_f32_e32 v171, v171, v95
	v_cvt_pk_bf16_f32 v231, v66, v67
	s_add_i32 s4, s4, 1
	s_cmp_lt_u32 s4, s39
	s_cbranch_scc0 .Lp11_drain
; #define A64_GLOAD(t) do { A64_IDX(); const char* Kt = (const char*)(Kg + (size_t)(t) * 64 * ldk); const char* Vt = (const char*)(Vg + (size_t)(t) * 64 * ldv); \
;         kreg0 = *(const u32x4*)(Kt + (unsigned)(kk0 * ldk + kc0 * 8) * 2u); if (k2) kreg1 = *(const u32x4*)(Kt + (unsigned)(kk1 * ldk + kc1 * 8) * 2u); vreg = *(const u32x4*)(Vt + (unsigned)(vk * ldv + vc * 8) * 2u); } while (0)
; #define A64_LWRITE(bo) do { A64_IDX(); *(LAS u32x4*)(lds + (bo) + kk0 * KP + kc0 * 16) = kreg0; if (k2) *(LAS u32x4*)(lds + (bo) + kk1 * KP + kc1 * 16) = kreg1; \
;         *(LAS u32x4*)(lds + (bo) + KBYTES + (vc >> 2) * 4096 + vk * 64 + (vc & 3) * 16) = vreg; } while (0)
; #define A64_KREAD(bo, half) do { _Pragma("unroll") for (int ds = 0; ds < NDS; ++ds) kf[ds] = *(const LAS bf16x8*)(lds + (bo) + kfr + (half) * 32 * KP + ds * 32); } while (0)
; #define A64_S(dst, q) do { _Pragma("unroll") for (int i = 0; i < 16; ++i) dst[i] = 0.f; _Pragma("unroll") for (int ds = 0; ds < NDS; ++ds) dst = __builtin_amdgcn_mfma_f32_32x32x16_bf16(kf[ds], q[ds], dst, 0, 0, 0); } while (0)
; #define A64_SB() __builtin_amdgcn_sched_barrier(0)
; template <int DQK>
; __device__ __forceinline__ void attn_unit64p(LAS char* lds, const bf16x8 (&qa)[DQK / 16], const bf16x8 (&qb)[DQK / 16],
;                                              const bf16_t* Kg, int ldk, const bf16_t* Vg, int ldv, int nt, bf16_t* Obase, int ldo, int ogb_off) {
;     ...
;     A64_GLOAD(0); A64_LWRITE(0);
;     __syncthreads();
;     if (nt > 1) A64_GLOAD(1);
;     A64_KREAD(0, 0);
; #pragma nounroll
;     for (int j = 0; j < 2 * nt; ++j) {
;         const int t = j >> 1, hf = j & 1;
;         const unsigned bo = (t & 1) * BUF, bn = ((t & 1) ^ 1) * BUF;
;         const unsigned vo = bo + hf * 2048;
;         const unsigned ko = hf ? bn : bo + 32 * KP;
;         A64_SB(); A64_S(sa, qa); A64_EXP(sb, lb0, lb1, pb);
;         A64_SB(); A64_PV(ob0, ob1, pb);
;         A64_SB(); A64_S(sb, qb); A64_EXP(sa, la0, la1, pa); A64_VREAD(vo, 0);
;         A64_SB(); A64_KREAD(ko, 0); A64_PV(oa0, oa1, pa);
;         A64_SB();
;         if (!hf) {
;             if (t + 1 < nt) A64_LWRITE(bn);
;             __syncthreads();
;             if (t + 2 < nt) A64_GLOAD(t + 2);
;         }
;     }
	s_waitcnt lgkmcnt(0)
	v_mfma_f32_32x32x16_bf16 v[80:95], v[182:185], v[128:131], 0
	v_exp_f32_e32 v68, v68
	v_add_f32_e32 v172, v172, v64
	v_exp_f32_e32 v69, v69
	v_add_f32_e32 v173, v173, v65
	v_mfma_f32_32x32x16_bf16 v[80:95], v[186:189], v[124:127], v[80:95]
	v_exp_f32_e32 v70, v70
	v_cvt_pk_bf16_f32 v232, v68, v69
	v_exp_f32_e32 v71, v71
	v_add_f32_e32 v172, v172, v66
	v_mfma_f32_32x32x16_bf16 v[80:95], v[190:193], v[120:123], v[80:95]
	v_exp_f32_e32 v72, v72
	v_cvt_pk_bf16_f32 v233, v70, v71
	v_exp_f32_e32 v73, v73
	v_add_f32_e32 v173, v173, v67
	v_mfma_f32_32x32x16_bf16 v[80:95], v[194:197], v[116:119], v[80:95]
	v_exp_f32_e32 v74, v74
	v_cvt_pk_bf16_f32 v234, v72, v73
	v_exp_f32_e32 v75, v75
	v_add_f32_e32 v172, v172, v68
	v_mfma_f32_32x32x16_bf16 v[80:95], v[198:201], v[108:111], v[80:95]
	v_exp_f32_e32 v76, v76
	v_cvt_pk_bf16_f32 v235, v74, v75
	v_exp_f32_e32 v77, v77
	v_add_f32_e32 v173, v173, v69
	v_mfma_f32_32x32x16_bf16 v[80:95], v[202:205], v[112:115], v[80:95]
	v_exp_f32_e32 v78, v78
	v_cvt_pk_bf16_f32 v236, v76, v77
	v_exp_f32_e32 v79, v79
	v_add_f32_e32 v172, v172, v70
	v_mfma_f32_32x32x16_bf16 v[16:31], v[248:251], v[230:233], v[16:31]
	ds_read_b64_tr_b16 v[248:249], v239 offset:56320
	ds_read_b64_tr_b16 v[250:251], v239 offset:56832
	v_cvt_pk_bf16_f32 v237, v78, v79
	v_add_f32_e32 v173, v173, v71
	v_add_f32_e32 v172, v172, v72
	v_add_f32_e32 v173, v173, v73
	v_mfma_f32_32x32x16_bf16 v[0:15], v[252:255], v[230:233], v[0:15]
	ds_read_b64_tr_b16 v[252:253], v239 offset:60416
	ds_read_b64_tr_b16 v[254:255], v239 offset:60928
	v_add_f32_e32 v172, v172, v74
	v_exp_f32_e32 v80, v80
	v_add_f32_e32 v173, v173, v75
	v_exp_f32_e32 v81, v81
	v_mfma_f32_32x32x16_bf16 v[16:31], v[214:217], v[234:237], v[16:31]
	ds_read_b64_tr_b16 v[214:215], v239 offset:57344
	ds_read_b64_tr_b16 v[216:217], v239 offset:57856
	v_add_f32_e32 v172, v172, v76
	v_exp_f32_e32 v82, v82
	v_add_f32_e32 v173, v173, v77
	v_cvt_pk_bf16_f32 v222, v80, v81
	v_mfma_f32_32x32x16_bf16 v[0:15], v[218:221], v[234:237], v[0:15]
	ds_read_b64_tr_b16 v[218:219], v239 offset:61440
	ds_read_b64_tr_b16 v[220:221], v239 offset:61952
	v_exp_f32_e32 v83, v83
	v_add_f32_e32 v172, v172, v78
	v_add_f32_e32 v173, v173, v79
	v_cvt_pk_bf16_f32 v223, v82, v83
	v_mfma_f32_32x32x16_bf16 v[64:79], v[182:185], v[132:135], 0
	ds_read_b128 v[182:185], v238 offset:49664
	v_exp_f32_e32 v84, v84
	v_add_f32_e32 v170, v170, v80
	v_exp_f32_e32 v85, v85
	v_add_f32_e32 v171, v171, v81
	v_mfma_f32_32x32x16_bf16 v[64:79], v[186:189], v[136:139], v[64:79]
	ds_read_b128 v[186:189], v238 offset:49696
	v_exp_f32_e32 v86, v86
	v_cvt_pk_bf16_f32 v224, v84, v85
	v_exp_f32_e32 v87, v87
	v_add_f32_e32 v170, v170, v82
	v_mfma_f32_32x32x16_bf16 v[64:79], v[190:193], v[140:143], v[64:79]
	ds_read_b128 v[190:193], v238 offset:49728
	v_exp_f32_e32 v88, v88
	v_cvt_pk_bf16_f32 v225, v86, v87
	v_exp_f32_e32 v89, v89
	v_add_f32_e32 v171, v171, v83
	v_mfma_f32_32x32x16_bf16 v[64:79], v[194:197], v[144:147], v[64:79]
	ds_read_b128 v[194:197], v238 offset:49760
	v_exp_f32_e32 v90, v90
	v_cvt_pk_bf16_f32 v226, v88, v89
	v_exp_f32_e32 v91, v91
	v_add_f32_e32 v170, v170, v84
	v_mfma_f32_32x32x16_bf16 v[64:79], v[198:201], v[148:151], v[64:79]
	ds_read_b128 v[198:201], v238 offset:49792
	v_exp_f32_e32 v92, v92
	v_cvt_pk_bf16_f32 v227, v90, v91
	v_exp_f32_e32 v93, v93
	v_add_f32_e32 v171, v171, v85
	v_mfma_f32_32x32x16_bf16 v[64:79], v[202:205], v[152:155], v[64:79]
	ds_read_b128 v[202:205], v238 offset:49824
	v_exp_f32_e32 v94, v94
	v_cvt_pk_bf16_f32 v228, v92, v93
	v_exp_f32_e32 v95, v95
	v_add_f32_e32 v170, v170, v86
	s_waitcnt lgkmcnt(6)
	v_mfma_f32_32x32x16_bf16 v[32:47], v[248:251], v[222:225], v[32:47]
	v_cvt_pk_bf16_f32 v229, v94, v95
	v_add_f32_e32 v171, v171, v87
	v_add_f32_e32 v170, v170, v88
	v_add_f32_e32 v171, v171, v89
	s_waitcnt vmcnt(0)
	ds_write_b128 v159, v[96:99] offset:0
	s_cmp_eq_u64 s[0:1], 0
	v_mfma_f32_32x32x16_bf16 v[48:63], v[252:255], v[222:225], v[48:63]
	v_add_f32_e32 v170, v170, v90
	v_exp_f32_e32 v64, v64
	v_add_f32_e32 v171, v171, v91
	v_exp_f32_e32 v65, v65
	s_cbranch_scc1 .Lp11_w1_a2
	ds_write_b128 v212, v[100:103] offset:0
.Lp11_w1_a2:
	ds_write_b128 v179, v[104:107] offset:13312
	v_mfma_f32_32x32x16_bf16 v[32:47], v[214:217], v[226:229], v[32:47]
	v_add_f32_e32 v170, v170, v92
	v_exp_f32_e32 v66, v66
	v_add_f32_e32 v171, v171, v93
	v_cvt_pk_bf16_f32 v230, v64, v65
	s_add_u32 s22, s22, 0x3000
	s_addc_u32 s23, s23, 0
	v_lshl_add_u64 v[180:181], v[180:181], 0, s[24:25]
	v_mfma_f32_32x32x16_bf16 v[48:63], v[218:221], v[226:229], v[48:63]
	v_exp_f32_e32 v67, v67
	v_add_f32_e32 v170, v170, v94
	v_add_f32_e32 v171, v171, v95
	v_cvt_pk_bf16_f32 v231, v66, v67
	global_load_dwordx4 v[96:99], v160, s[22:23]
	s_cmp_eq_u64 s[0:1], 0
	s_cbranch_scc1 .Lp11_g1_a2
	global_load_dwordx4 v[100:103], v166, s[22:23]
; #define A64_GLOAD(t) do { A64_IDX(); const char* Kt = (const char*)(Kg + (size_t)(t) * 64 * ldk); const char* Vt = (const char*)(Vg + (size_t)(t) * 64 * ldv); \
;         kreg0 = *(const u32x4*)(Kt + (unsigned)(kk0 * ldk + kc0 * 8) * 2u); if (k2) kreg1 = *(const u32x4*)(Kt + (unsigned)(kk1 * ldk + kc1 * 8) * 2u); vreg = *(const u32x4*)(Vt + (unsigned)(vk * ldv + vc * 8) * 2u); } while (0)
; #define A64_LWRITE(bo) do { A64_IDX(); *(LAS u32x4*)(lds + (bo) + kk0 * KP + kc0 * 16) = kreg0; if (k2) *(LAS u32x4*)(lds + (bo) + kk1 * KP + kc1 * 16) = kreg1; \
;         *(LAS u32x4*)(lds + (bo) + KBYTES + (vc >> 2) * 4096 + vk * 64 + (vc & 3) * 16) = vreg; } while (0)
; #define A64_KREAD(bo, half) do { _Pragma("unroll") for (int ds = 0; ds < NDS; ++ds) kf[ds] = *(const LAS bf16x8*)(lds + (bo) + kfr + (half) * 32 * KP + ds * 32); } while (0)
; #define A64_S(dst, q) do { _Pragma("unroll") for (int i = 0; i < 16; ++i) dst[i] = 0.f; _Pragma("unroll") for (int ds = 0; ds < NDS; ++ds) dst = __builtin_amdgcn_mfma_f32_32x32x16_bf16(kf[ds], q[ds], dst, 0, 0, 0); } while (0)
; #define A64_SB() __builtin_amdgcn_sched_barrier(0)
; template <int DQK>
; __device__ __forceinline__ void attn_unit64p(LAS char* lds, const bf16x8 (&qa)[DQK / 16], const bf16x8 (&qb)[DQK / 16],
;                                              const bf16_t* Kg, int ldk, const bf16_t* Vg, int ldv, int nt, bf16_t* Obase, int ldo, int ogb_off) {
;     ...
;     A64_GLOAD(0); A64_LWRITE(0);
;     __syncthreads();
;     if (nt > 1) A64_GLOAD(1);
;     A64_KREAD(0, 0);
; #pragma nounroll
;     for (int j = 0; j < 2 * nt; ++j) {
;         const int t = j >> 1, hf = j & 1;
;         const unsigned bo = (t & 1) * BUF, bn = ((t & 1) ^ 1) * BUF;
;         const unsigned vo = bo + hf * 2048;
;         const unsigned ko = hf ? bn : bo + 32 * KP;
;         A64_SB(); A64_S(sa, qa); A64_EXP(sb, lb0, lb1, pb);
;         A64_SB(); A64_PV(ob0, ob1, pb);
;         A64_SB(); A64_S(sb, qb); A64_EXP(sa, la0, la1, pa); A64_VREAD(vo, 0);
;         A64_SB(); A64_KREAD(ko, 0); A64_PV(oa0, oa1, pa);
;         A64_SB();
;         if (!hf) {
;             if (t + 1 < nt) A64_LWRITE(bn);
;             __syncthreads();
;             if (t + 2 < nt) A64_GLOAD(t + 2);
;         }
;     }
;     A64_SB(); A64_EXP(sb, lb0, lb1, pb); A64_PV(ob0, ob1, pb);
.Lp11_g1_a2:
	global_load_dwordx4 v[104:107], v[180:181], off
	s_waitcnt lgkmcnt(2)
	v_mfma_f32_32x32x16_bf16 v[80:95], v[182:185], v[128:131], 0
	v_exp_f32_e32 v68, v68
	v_add_f32_e32 v172, v172, v64
	v_exp_f32_e32 v69, v69
	v_add_f32_e32 v173, v173, v65
	v_mfma_f32_32x32x16_bf16 v[80:95], v[186:189], v[124:127], v[80:95]
	v_exp_f32_e32 v70, v70
	v_cvt_pk_bf16_f32 v232, v68, v69
	v_exp_f32_e32 v71, v71
	v_add_f32_e32 v172, v172, v66
	v_mfma_f32_32x32x16_bf16 v[80:95], v[190:193], v[120:123], v[80:95]
	v_exp_f32_e32 v72, v72
	v_cvt_pk_bf16_f32 v233, v70, v71
	v_exp_f32_e32 v73, v73
	v_add_f32_e32 v173, v173, v67
	v_mfma_f32_32x32x16_bf16 v[80:95], v[194:197], v[116:119], v[80:95]
	v_exp_f32_e32 v74, v74
	v_cvt_pk_bf16_f32 v234, v72, v73
	v_exp_f32_e32 v75, v75
	v_add_f32_e32 v172, v172, v68
	v_mfma_f32_32x32x16_bf16 v[80:95], v[198:201], v[108:111], v[80:95]
	v_exp_f32_e32 v76, v76
	v_cvt_pk_bf16_f32 v235, v74, v75
	v_exp_f32_e32 v77, v77
	v_add_f32_e32 v173, v173, v69
	v_mfma_f32_32x32x16_bf16 v[80:95], v[202:205], v[112:115], v[80:95]
	v_exp_f32_e32 v78, v78
	v_cvt_pk_bf16_f32 v236, v76, v77
	v_exp_f32_e32 v79, v79
	v_add_f32_e32 v172, v172, v70
	v_mfma_f32_32x32x16_bf16 v[16:31], v[248:251], v[230:233], v[16:31]
	ds_read_b64_tr_b16 v[248:249], v239 offset:58368
	ds_read_b64_tr_b16 v[250:251], v239 offset:58880
	v_cvt_pk_bf16_f32 v237, v78, v79
	v_add_f32_e32 v173, v173, v71
	v_add_f32_e32 v172, v172, v72
	v_add_f32_e32 v173, v173, v73
	v_mfma_f32_32x32x16_bf16 v[0:15], v[252:255], v[230:233], v[0:15]
	ds_read_b64_tr_b16 v[252:253], v239 offset:62464
	ds_read_b64_tr_b16 v[254:255], v239 offset:62976
	v_add_f32_e32 v172, v172, v74
	v_exp_f32_e32 v80, v80
	v_add_f32_e32 v173, v173, v75
	v_exp_f32_e32 v81, v81
	v_mfma_f32_32x32x16_bf16 v[16:31], v[214:217], v[234:237], v[16:31]
	ds_read_b64_tr_b16 v[214:215], v239 offset:59392
	ds_read_b64_tr_b16 v[216:217], v239 offset:59904
	v_add_f32_e32 v172, v172, v76
	v_exp_f32_e32 v82, v82
	v_add_f32_e32 v173, v173, v77
	v_cvt_pk_bf16_f32 v222, v80, v81
	v_mfma_f32_32x32x16_bf16 v[0:15], v[218:221], v[234:237], v[0:15]
	ds_read_b64_tr_b16 v[218:219], v239 offset:63488
	ds_read_b64_tr_b16 v[220:221], v239 offset:64000
	v_exp_f32_e32 v83, v83
	v_add_f32_e32 v172, v172, v78
	v_add_f32_e32 v173, v173, v79
	v_cvt_pk_bf16_f32 v223, v82, v83
	s_waitcnt lgkmcnt(8)
	s_barrier
	v_mfma_f32_32x32x16_bf16 v[64:79], v[182:185], v[132:135], 0
	ds_read_b128 v[182:185], v238
	v_exp_f32_e32 v84, v84
	v_add_f32_e32 v170, v170, v80
	v_exp_f32_e32 v85, v85
	v_add_f32_e32 v171, v171, v81
	v_mfma_f32_32x32x16_bf16 v[64:79], v[186:189], v[136:139], v[64:79]
	ds_read_b128 v[186:189], v238 offset:32
	v_exp_f32_e32 v86, v86
	v_cvt_pk_bf16_f32 v224, v84, v85
	v_exp_f32_e32 v87, v87
	v_add_f32_e32 v170, v170, v82
	v_mfma_f32_32x32x16_bf16 v[64:79], v[190:193], v[140:143], v[64:79]
	ds_read_b128 v[190:193], v238 offset:64
	v_exp_f32_e32 v88, v88
	v_cvt_pk_bf16_f32 v225, v86, v87
	v_exp_f32_e32 v89, v89
	v_add_f32_e32 v171, v171, v83
	v_mfma_f32_32x32x16_bf16 v[64:79], v[194:197], v[144:147], v[64:79]
	ds_read_b128 v[194:197], v238 offset:96
	v_exp_f32_e32 v90, v90
	v_cvt_pk_bf16_f32 v226, v88, v89
	v_exp_f32_e32 v91, v91
	v_add_f32_e32 v170, v170, v84
	v_mfma_f32_32x32x16_bf16 v[64:79], v[198:201], v[148:151], v[64:79]
	ds_read_b128 v[198:201], v238 offset:128
	v_exp_f32_e32 v92, v92
	v_cvt_pk_bf16_f32 v227, v90, v91
	v_exp_f32_e32 v93, v93
	v_add_f32_e32 v171, v171, v85
	v_mfma_f32_32x32x16_bf16 v[64:79], v[202:205], v[152:155], v[64:79]
	ds_read_b128 v[202:205], v238 offset:160
	v_exp_f32_e32 v94, v94
	v_cvt_pk_bf16_f32 v228, v92, v93
	v_exp_f32_e32 v95, v95
	v_add_f32_e32 v170, v170, v86
	s_waitcnt lgkmcnt(6)
	v_mfma_f32_32x32x16_bf16 v[32:47], v[248:251], v[222:225], v[32:47]
	v_cvt_pk_bf16_f32 v229, v94, v95
	v_add_f32_e32 v171, v171, v87
	v_add_f32_e32 v170, v170, v88
	v_add_f32_e32 v171, v171, v89
	v_mfma_f32_32x32x16_bf16 v[48:63], v[252:255], v[222:225], v[48:63]
	v_add_f32_e32 v170, v170, v90
	v_exp_f32_e32 v64, v64
	v_add_f32_e32 v171, v171, v91
	v_exp_f32_e32 v65, v65
	v_mfma_f32_32x32x16_bf16 v[32:47], v[214:217], v[226:229], v[32:47]
	v_add_f32_e32 v170, v170, v92
	v_exp_f32_e32 v66, v66
	v_add_f32_e32 v171, v171, v93
	v_cvt_pk_bf16_f32 v230, v64, v65
	v_mfma_f32_32x32x16_bf16 v[48:63], v[218:221], v[226:229], v[48:63]
	v_exp_f32_e32 v67, v67
	v_add_f32_e32 v170, v170, v94
	v_add_f32_e32 v171, v171, v95
	v_cvt_pk_bf16_f32 v231, v66, v67
	s_add_i32 s4, s4, 1
	s_cmp_lt_u32 s4, s39
	s_cbranch_scc1 .Lp11_loop
.Lp11_drain:
	v_exp_f32_e32 v68, v68
	v_add_f32_e32 v172, v172, v64
	v_exp_f32_e32 v69, v69
	v_add_f32_e32 v173, v173, v65
	v_exp_f32_e32 v70, v70
	v_cvt_pk_bf16_f32 v232, v68, v69
	v_exp_f32_e32 v71, v71
	v_add_f32_e32 v172, v172, v66
	v_exp_f32_e32 v72, v72
	v_cvt_pk_bf16_f32 v233, v70, v71
	v_exp_f32_e32 v73, v73
	v_add_f32_e32 v173, v173, v67
	v_exp_f32_e32 v74, v74
	v_cvt_pk_bf16_f32 v234, v72, v73
	v_exp_f32_e32 v75, v75
	v_add_f32_e32 v172, v172, v68
	v_exp_f32_e32 v76, v76
	v_cvt_pk_bf16_f32 v235, v74, v75
	v_exp_f32_e32 v77, v77
	v_add_f32_e32 v173, v173, v69
	v_exp_f32_e32 v78, v78
	v_cvt_pk_bf16_f32 v236, v76, v77
	v_exp_f32_e32 v79, v79
	v_add_f32_e32 v172, v172, v70
	v_cvt_pk_bf16_f32 v237, v78, v79
	v_add_f32_e32 v173, v173, v71
	v_add_f32_e32 v172, v172, v72
	v_add_f32_e32 v173, v173, v73
	v_add_f32_e32 v172, v172, v74
	v_add_f32_e32 v173, v173, v75
	v_add_f32_e32 v172, v172, v76
	v_add_f32_e32 v173, v173, v77
	v_add_f32_e32 v172, v172, v78
	v_add_f32_e32 v173, v173, v79
	s_nop 1
	v_mfma_f32_32x32x16_bf16 v[16:31], v[248:251], v[230:233], v[16:31]
	v_mfma_f32_32x32x16_bf16 v[0:15], v[252:255], v[230:233], v[0:15]
	v_mfma_f32_32x32x16_bf16 v[16:31], v[214:217], v[234:237], v[16:31]
	v_mfma_f32_32x32x16_bf16 v[0:15], v[218:221], v[234:237], v[0:15]
	s_waitcnt vmcnt(0)
	s_waitcnt lgkmcnt(0)
	s_barrier
	s_branch .LBB0_1115
